# non-temporal loads of the read-once f32 weights and x rows in the first phase, non-temporal stores of the final f32 output
# speedup vs baseline: 1.0180x; 1.0180x over previous
.LBB0_20:
	s_movk_i32 s3, 0x2bff
	v_cmp_lt_i32_e32 vcc, s3, v16
	s_and_saveexec_b64 s[30:31], vcc
	s_xor_b64 s[30:31], exec, s[30:31]
	s_cbranch_execz .LBB0_37
	s_movk_i32 s3, 0x41ff
	v_cmp_lt_u32_e32 vcc, s3, v16
	s_and_saveexec_b64 s[60:61], vcc
	s_xor_b64 s[60:61], exec, s[60:61]
	s_cbranch_execz .LBB0_34
	s_movk_i32 s3, 0x49ff
	v_cmp_lt_u32_e32 vcc, s3, v16
	s_and_saveexec_b64 s[62:63], vcc
	s_xor_b64 s[62:63], exec, s[62:63]
	s_cbranch_execz .LBB0_28
	s_movk_i32 s3, 0x4dff
	v_and_b32_e32 v2, 0x3e0, v14
	v_cmp_lt_u32_e32 vcc, s3, v16
	v_lshlrev_b32_e32 v6, 2, v2
	v_or_b32_e32 v11, v2, v101
	v_or_b32_e32 v10, v2, v103
	v_or_b32_e32 v9, v2, v104
	v_or_b32_e32 v8, v2, v105
	s_and_saveexec_b64 s[64:65], vcc
	s_xor_b64 s[64:65], exec, s[64:65]
	s_cbranch_execz .LBB0_25
	v_and_b32_e32 v2, 0x7fffffc0, v15
	v_add_u32_e32 v4, 0xffff6400, v2
	v_or_b32_e32 v2, v4, v73
	v_lshlrev_b64 v[12:13], 12, v[2:3]
	s_waitcnt lgkmcnt(0)
	v_lshl_add_u64 v[12:13], s[26:27], 0, v[12:13]
	v_mov_b32_e32 v7, v3
	v_lshl_add_u64 v[6:7], v[12:13], 0, v[6:7]
	v_lshlrev_b32_e32 v2, 2, v70
	v_lshl_add_u64 v[6:7], v[6:7], 0, v[2:3]
	v_add_co_u32_e32 v12, vcc, 0x2000, v6
	v_mov_b32_e32 v5, v3
	s_nop 0
	v_addc_co_u32_e32 v13, vcc, 0, v7, vcc
	v_add_co_u32_e32 v18, vcc, 0x4000, v6
	s_nop 1
	v_addc_co_u32_e32 v19, vcc, 0, v7, vcc
	v_add_co_u32_e32 v20, vcc, 0x6000, v6
	s_nop 1
	v_addc_co_u32_e32 v21, vcc, 0, v7, vcc
	v_add_co_u32_e32 v22, vcc, 0x8000, v6
	s_nop 1
	v_addc_co_u32_e32 v23, vcc, 0, v7, vcc
	v_add_co_u32_e32 v24, vcc, 0xa000, v6
	s_nop 1
	v_addc_co_u32_e32 v25, vcc, 0, v7, vcc
	v_add_co_u32_e32 v26, vcc, 0xc000, v6
	s_nop 1
	v_addc_co_u32_e32 v27, vcc, 0, v7, vcc
	v_add_co_u32_e32 v28, vcc, 0xe000, v6
	s_nop 1
	v_addc_co_u32_e32 v29, vcc, 0, v7, vcc
	global_load_dword v2, v[6:7], off nt
	global_load_dword v17, v[12:13], off nt
	global_load_dword v32, v[18:19], off nt
	global_load_dword v33, v[20:21], off nt
	global_load_dword v34, v[22:23], off nt
	global_load_dword v35, v[24:25], off nt
	global_load_dword v36, v[26:27], off nt
	global_load_dword v37, v[28:29], off nt
	v_add_co_u32_e32 v12, vcc, 0x10000, v6
	s_nop 1
	v_addc_co_u32_e32 v13, vcc, 0, v7, vcc
	v_add_co_u32_e32 v18, vcc, 0x12000, v6
	s_nop 1
	v_addc_co_u32_e32 v19, vcc, 0, v7, vcc
	v_add_co_u32_e32 v20, vcc, 0x14000, v6
	s_nop 1
	v_addc_co_u32_e32 v21, vcc, 0, v7, vcc
	v_add_co_u32_e32 v22, vcc, 0x16000, v6
	s_nop 1
	v_addc_co_u32_e32 v23, vcc, 0, v7, vcc
	v_add_co_u32_e32 v24, vcc, 0x18000, v6
	s_nop 1
	v_addc_co_u32_e32 v25, vcc, 0, v7, vcc
	v_add_co_u32_e32 v26, vcc, 0x1a000, v6
	s_nop 1
	v_addc_co_u32_e32 v27, vcc, 0, v7, vcc
	v_add_co_u32_e32 v28, vcc, 0x1c000, v6
	s_nop 1
	v_addc_co_u32_e32 v29, vcc, 0, v7, vcc
	v_add_co_u32_e32 v30, vcc, 0x1e000, v6
	s_nop 1
	v_addc_co_u32_e32 v31, vcc, 0, v7, vcc
	global_load_dword v38, v[12:13], off nt
	global_load_dword v39, v[18:19], off nt
	global_load_dword v40, v[20:21], off nt
	global_load_dword v41, v[22:23], off nt
	global_load_dword v42, v[24:25], off nt
	global_load_dword v43, v[26:27], off nt
	global_load_dword v44, v[28:29], off nt
	global_load_dword v45, v[30:31], off nt
	v_add_co_u32_e32 v12, vcc, s75, v6
	s_nop 1
	v_addc_co_u32_e32 v13, vcc, 0, v7, vcc
	v_add_co_u32_e32 v18, vcc, 0x22000, v6
	s_nop 1
	v_addc_co_u32_e32 v19, vcc, 0, v7, vcc
	v_add_co_u32_e32 v20, vcc, 0x24000, v6
	s_nop 1
	v_addc_co_u32_e32 v21, vcc, 0, v7, vcc
	v_add_co_u32_e32 v22, vcc, 0x26000, v6
	s_nop 1
	v_addc_co_u32_e32 v23, vcc, 0, v7, vcc
	v_add_co_u32_e32 v24, vcc, 0x28000, v6
	s_nop 1
	v_addc_co_u32_e32 v25, vcc, 0, v7, vcc
	v_add_co_u32_e32 v26, vcc, 0x2a000, v6
	s_nop 1
	v_addc_co_u32_e32 v27, vcc, 0, v7, vcc
	v_add_co_u32_e32 v28, vcc, 0x2c000, v6
	s_nop 1
	v_addc_co_u32_e32 v29, vcc, 0, v7, vcc
	v_add_co_u32_e32 v30, vcc, 0x2e000, v6
	s_nop 1
	v_addc_co_u32_e32 v31, vcc, 0, v7, vcc
	global_load_dword v46, v[12:13], off nt
	global_load_dword v47, v[18:19], off nt
	global_load_dword v48, v[20:21], off nt
	global_load_dword v49, v[22:23], off nt
	global_load_dword v50, v[24:25], off nt
	global_load_dword v51, v[26:27], off nt
	global_load_dword v52, v[28:29], off nt
	s_nop 0
	global_load_dword v30, v[30:31], off nt
	v_add_co_u32_e32 v12, vcc, 0x30000, v6
	s_nop 1
	v_addc_co_u32_e32 v13, vcc, 0, v7, vcc
	v_add_co_u32_e32 v18, vcc, 0x32000, v6
	s_nop 1
	v_addc_co_u32_e32 v19, vcc, 0, v7, vcc
	v_add_co_u32_e32 v20, vcc, 0x34000, v6
	s_nop 1
	v_addc_co_u32_e32 v21, vcc, 0, v7, vcc
	v_add_co_u32_e32 v22, vcc, 0x36000, v6
	s_nop 1
	v_addc_co_u32_e32 v23, vcc, 0, v7, vcc
	v_add_co_u32_e32 v24, vcc, 0x38000, v6
	s_nop 1
	v_addc_co_u32_e32 v25, vcc, 0, v7, vcc
	v_add_co_u32_e32 v26, vcc, 0x3a000, v6
	s_nop 1
	v_addc_co_u32_e32 v27, vcc, 0, v7, vcc
	v_add_co_u32_e32 v28, vcc, 0x3c000, v6
	s_nop 1
	v_addc_co_u32_e32 v29, vcc, 0, v7, vcc
	v_add_co_u32_e32 v6, vcc, s79, v6
	s_nop 1
	v_addc_co_u32_e32 v7, vcc, 0, v7, vcc
	global_load_dword v12, v[12:13], off nt
	s_nop 0
	global_load_dword v13, v[18:19], off nt
	global_load_dword v31, v[20:21], off nt
	global_load_dword v53, v[22:23], off nt
	global_load_dword v54, v[24:25], off nt
	s_nop 0
	global_load_dword v26, v[26:27], off nt
	s_nop 0
	global_load_dword v27, v[28:29], off nt
	s_nop 0
	global_load_dword v28, v[6:7], off nt
	v_lshl_add_u64 v[6:7], v[4:5], 2, v[76:77]
	global_load_dwordx4 v[18:21], v[6:7], off
	global_load_dwordx4 v[22:25], v[6:7], off offset:16
	s_waitcnt vmcnt(32)
	ds_write2_b32 v100, v2, v17 offset1:66
	s_waitcnt vmcnt(30)
	ds_write2_b32 v100, v32, v33 offset0:132 offset1:198
	v_add_u32_e32 v2, 0x400, v100
	s_waitcnt vmcnt(28)
	ds_write2_b32 v2, v34, v35 offset0:8 offset1:74
	s_waitcnt vmcnt(26)
	ds_write2_b32 v2, v36, v37 offset0:140 offset1:206
	v_add_u32_e32 v2, 0x800, v100
	s_waitcnt vmcnt(24)
	ds_write2_b32 v2, v38, v39 offset0:16 offset1:82
	s_waitcnt vmcnt(22)
	ds_write2_b32 v2, v40, v41 offset0:148 offset1:214
	v_add_u32_e32 v2, 0xc00, v100
	s_waitcnt vmcnt(20)
	ds_write2_b32 v2, v42, v43 offset0:24 offset1:90
	s_waitcnt vmcnt(18)
	ds_write2_b32 v2, v44, v45 offset0:156 offset1:222
	v_add_u32_e32 v2, 0x1000, v100
	s_waitcnt vmcnt(16)
	ds_write2_b32 v2, v46, v47 offset0:32 offset1:98
	s_waitcnt vmcnt(14)
	ds_write2_b32 v2, v48, v49 offset0:164 offset1:230
	v_add_u32_e32 v2, 0x1400, v100
	s_waitcnt vmcnt(12)
	ds_write2_b32 v2, v50, v51 offset0:40 offset1:106
	s_waitcnt vmcnt(10)
	ds_write2_b32 v2, v52, v30 offset0:172 offset1:238
	v_add_u32_e32 v2, 0x1800, v100
	s_waitcnt vmcnt(8)
	ds_write2_b32 v2, v12, v13 offset0:48 offset1:114
	s_waitcnt vmcnt(6)
	ds_write2_b32 v2, v31, v53 offset0:180 offset1:246
	v_add_u32_e32 v2, 0x1c00, v100
	s_waitcnt vmcnt(4)
	ds_write2_b32 v2, v54, v26 offset0:56 offset1:122
	s_waitcnt vmcnt(2)
	ds_write2_b32 v2, v27, v28 offset0:188 offset1:254
	s_waitcnt lgkmcnt(0)
	ds_read2_b32 v[6:7], v102 offset1:33
	v_lshl_add_u64 v[12:13], v[4:5], 1, v[78:79]
	s_waitcnt vmcnt(1) lgkmcnt(0)
	v_mul_f32_e32 v2, v18, v6
	v_mul_f32_e32 v6, v19, v7
	v_cvt_pk_bf16_f32 v26, v2, v6
	ds_read2_b32 v[6:7], v102 offset0:66 offset1:99
	s_waitcnt lgkmcnt(0)
	v_mul_f32_e32 v2, v20, v6
	v_mul_f32_e32 v6, v21, v7
	v_cvt_pk_bf16_f32 v27, v2, v6
	ds_read2_b32 v[6:7], v102 offset0:132 offset1:165
	s_waitcnt vmcnt(0) lgkmcnt(0)
	v_mul_f32_e32 v2, v22, v6
	v_mul_f32_e32 v6, v23, v7
	v_cvt_pk_bf16_f32 v28, v2, v6
	ds_read2_b32 v[6:7], v102 offset0:198 offset1:231
	s_waitcnt lgkmcnt(0)
	v_mul_f32_e32 v2, v24, v6
	v_mul_f32_e32 v6, v25, v7
	v_cvt_pk_bf16_f32 v29, v2, v6
	ds_read2_b32 v[6:7], v102 offset0:8 offset1:41
	v_lshlrev_b32_e32 v2, 11, v11
	v_lshl_add_u64 v[4:5], v[12:13], 0, v[2:3]
	global_store_dwordx4 v[4:5], v[26:29], off
	s_waitcnt lgkmcnt(0)
	v_mul_f32_e32 v4, v19, v7
	v_mul_f32_e32 v2, v18, v6
	v_cvt_pk_bf16_f32 v4, v2, v4
	ds_read2_b32 v[6:7], v102 offset0:74 offset1:107
	s_waitcnt lgkmcnt(0)
	v_mul_f32_e32 v5, v21, v7
	v_mul_f32_e32 v2, v20, v6
	v_cvt_pk_bf16_f32 v5, v2, v5
	ds_read2_b32 v[6:7], v102 offset0:140 offset1:173
	s_waitcnt lgkmcnt(0)
	v_mul_f32_e32 v2, v22, v6
	v_mul_f32_e32 v6, v23, v7
	v_cvt_pk_bf16_f32 v6, v2, v6
	ds_read2_b32 v[26:27], v102 offset0:206 offset1:239
	s_waitcnt lgkmcnt(0)
	v_mul_f32_e32 v7, v25, v27
	v_mul_f32_e32 v2, v24, v26
	v_cvt_pk_bf16_f32 v7, v2, v7
	ds_read2_b32 v[26:27], v102 offset0:16 offset1:49
	v_lshlrev_b32_e32 v2, 11, v10
	v_lshl_add_u64 v[10:11], v[12:13], 0, v[2:3]
	global_store_dwordx4 v[10:11], v[4:7], off
	s_waitcnt lgkmcnt(0)
	v_mul_f32_e32 v2, v18, v26
	v_mul_f32_e32 v4, v19, v27
	v_cvt_pk_bf16_f32 v4, v2, v4
	ds_read2_b32 v[6:7], v102 offset0:82 offset1:115
	s_waitcnt lgkmcnt(0)
	v_mul_f32_e32 v5, v21, v7
	v_mul_f32_e32 v2, v20, v6
	v_cvt_pk_bf16_f32 v5, v2, v5
	ds_read2_b32 v[6:7], v102 offset0:148 offset1:181
	s_waitcnt lgkmcnt(0)
	v_mul_f32_e32 v2, v22, v6
	v_mul_f32_e32 v6, v23, v7
	v_cvt_pk_bf16_f32 v6, v2, v6
	ds_read2_b32 v[10:11], v102 offset0:214 offset1:247
	s_waitcnt lgkmcnt(0)
	v_mul_f32_e32 v7, v25, v11
	v_mul_f32_e32 v2, v24, v10
	v_cvt_pk_bf16_f32 v7, v2, v7
	ds_read2_b32 v[10:11], v102 offset0:24 offset1:57
	v_lshlrev_b32_e32 v2, 11, v9
	v_lshl_add_u64 v[26:27], v[12:13], 0, v[2:3]
	global_store_dwordx4 v[26:27], v[4:7], off
	s_waitcnt lgkmcnt(0)
	v_mul_f32_e32 v2, v18, v10
	v_mul_f32_e32 v4, v19, v11
	v_cvt_pk_bf16_f32 v4, v2, v4
	ds_read2_b32 v[6:7], v102 offset0:90 offset1:123
	s_waitcnt lgkmcnt(0)
	v_mul_f32_e32 v5, v21, v7
	v_mul_f32_e32 v2, v20, v6
	v_cvt_pk_bf16_f32 v5, v2, v5
	ds_read2_b32 v[6:7], v102 offset0:156 offset1:189
	s_waitcnt lgkmcnt(0)
	v_mul_f32_e32 v2, v22, v6
	v_mul_f32_e32 v6, v23, v7
	v_cvt_pk_bf16_f32 v6, v2, v6
	ds_read2_b32 v[10:11], v102 offset0:222 offset1:255
	s_waitcnt lgkmcnt(0)
	v_mul_f32_e32 v2, v24, v10
	v_mul_f32_e32 v7, v25, v11
	v_cvt_pk_bf16_f32 v7, v2, v7
	v_lshlrev_b32_e32 v2, 11, v8
	v_lshl_add_u64 v[8:9], v[12:13], 0, v[2:3]
	global_store_dwordx4 v[8:9], v[4:7], off
	s_waitcnt lgkmcnt(0)
.LBB0_25:
	s_andn2_saveexec_b64 s[64:65], s[64:65]
	s_cbranch_execz .LBB0_27
	v_and_b32_e32 v2, 0xffc0, v15
	v_add_u32_e32 v4, 0xffff6c00, v2
	v_or_b32_e32 v2, v4, v73
	v_lshlrev_b64 v[12:13], 12, v[2:3]
	s_waitcnt lgkmcnt(0)
	v_lshl_add_u64 v[12:13], s[24:25], 0, v[12:13]
	v_mov_b32_e32 v7, v3
	v_lshl_add_u64 v[6:7], v[12:13], 0, v[6:7]
	v_lshlrev_b32_e32 v2, 2, v70
	v_lshl_add_u64 v[6:7], v[6:7], 0, v[2:3]
	v_add_co_u32_e32 v12, vcc, 0x2000, v6
	s_nop 1
	v_addc_co_u32_e32 v13, vcc, 0, v7, vcc
	v_add_co_u32_e32 v18, vcc, 0x4000, v6
	s_nop 1
	v_addc_co_u32_e32 v19, vcc, 0, v7, vcc
	v_add_co_u32_e32 v20, vcc, 0x6000, v6
	s_nop 1
	v_addc_co_u32_e32 v21, vcc, 0, v7, vcc
	v_add_co_u32_e32 v22, vcc, 0x8000, v6
	s_nop 1
	v_addc_co_u32_e32 v23, vcc, 0, v7, vcc
	v_add_co_u32_e32 v24, vcc, 0xa000, v6
	s_nop 1
	v_addc_co_u32_e32 v25, vcc, 0, v7, vcc
	v_add_co_u32_e32 v26, vcc, 0xc000, v6
	s_nop 1
	v_addc_co_u32_e32 v27, vcc, 0, v7, vcc
	v_add_co_u32_e32 v28, vcc, 0xe000, v6
	s_nop 1
	v_addc_co_u32_e32 v29, vcc, 0, v7, vcc
	global_load_dword v2, v[6:7], off nt
	global_load_dword v5, v[12:13], off nt
	global_load_dword v17, v[18:19], off nt
	global_load_dword v32, v[20:21], off nt
	global_load_dword v33, v[22:23], off nt
	global_load_dword v34, v[24:25], off nt
	global_load_dword v35, v[26:27], off nt
	global_load_dword v36, v[28:29], off nt
	v_add_co_u32_e32 v12, vcc, 0x10000, v6
	s_nop 1
	v_addc_co_u32_e32 v13, vcc, 0, v7, vcc
	v_add_co_u32_e32 v18, vcc, 0x12000, v6
	s_nop 1
	v_addc_co_u32_e32 v19, vcc, 0, v7, vcc
	v_add_co_u32_e32 v20, vcc, 0x14000, v6
	s_nop 1
	v_addc_co_u32_e32 v21, vcc, 0, v7, vcc
	v_add_co_u32_e32 v22, vcc, 0x16000, v6
	s_nop 1
	v_addc_co_u32_e32 v23, vcc, 0, v7, vcc
	v_add_co_u32_e32 v24, vcc, 0x18000, v6
	s_nop 1
	v_addc_co_u32_e32 v25, vcc, 0, v7, vcc
	v_add_co_u32_e32 v26, vcc, 0x1a000, v6
	s_nop 1
	v_addc_co_u32_e32 v27, vcc, 0, v7, vcc
	v_add_co_u32_e32 v28, vcc, 0x1c000, v6
	s_nop 1
	v_addc_co_u32_e32 v29, vcc, 0, v7, vcc
	v_add_co_u32_e32 v30, vcc, 0x1e000, v6
	s_nop 1
	v_addc_co_u32_e32 v31, vcc, 0, v7, vcc
	global_load_dword v37, v[12:13], off nt
	global_load_dword v38, v[18:19], off nt
	global_load_dword v39, v[20:21], off nt
	global_load_dword v40, v[22:23], off nt
	global_load_dword v41, v[24:25], off nt
	global_load_dword v42, v[26:27], off nt
	global_load_dword v43, v[28:29], off nt
	global_load_dword v44, v[30:31], off nt
	v_add_co_u32_e32 v12, vcc, s75, v6
	s_nop 1
	v_addc_co_u32_e32 v13, vcc, 0, v7, vcc
	v_add_co_u32_e32 v18, vcc, 0x22000, v6
	s_nop 1
	v_addc_co_u32_e32 v19, vcc, 0, v7, vcc
	v_add_co_u32_e32 v20, vcc, 0x24000, v6
	s_nop 1
	v_addc_co_u32_e32 v21, vcc, 0, v7, vcc
	v_add_co_u32_e32 v22, vcc, 0x26000, v6
	s_nop 1
	v_addc_co_u32_e32 v23, vcc, 0, v7, vcc
	v_add_co_u32_e32 v24, vcc, 0x28000, v6
	s_nop 1
	v_addc_co_u32_e32 v25, vcc, 0, v7, vcc
	v_add_co_u32_e32 v26, vcc, 0x2a000, v6
	s_nop 1
	v_addc_co_u32_e32 v27, vcc, 0, v7, vcc
	v_add_co_u32_e32 v28, vcc, 0x2c000, v6
	s_nop 1
	v_addc_co_u32_e32 v29, vcc, 0, v7, vcc
	v_add_co_u32_e32 v30, vcc, 0x2e000, v6
	s_nop 1
	v_addc_co_u32_e32 v31, vcc, 0, v7, vcc
	global_load_dword v45, v[12:13], off nt
	global_load_dword v46, v[18:19], off nt
	global_load_dword v47, v[20:21], off nt
	global_load_dword v48, v[22:23], off nt
	global_load_dword v49, v[24:25], off nt
	global_load_dword v50, v[26:27], off nt
	global_load_dword v51, v[28:29], off nt
	s_nop 0
	global_load_dword v30, v[30:31], off nt
	v_add_co_u32_e32 v12, vcc, 0x30000, v6
	s_nop 1
	v_addc_co_u32_e32 v13, vcc, 0, v7, vcc
	v_add_co_u32_e32 v18, vcc, 0x32000, v6
	s_nop 1
	v_addc_co_u32_e32 v19, vcc, 0, v7, vcc
	v_add_co_u32_e32 v20, vcc, 0x34000, v6
	s_nop 1
	v_addc_co_u32_e32 v21, vcc, 0, v7, vcc
	v_add_co_u32_e32 v22, vcc, 0x36000, v6
	s_nop 1
	v_addc_co_u32_e32 v23, vcc, 0, v7, vcc
	v_add_co_u32_e32 v24, vcc, 0x38000, v6
	s_nop 1
	v_addc_co_u32_e32 v25, vcc, 0, v7, vcc
	v_add_co_u32_e32 v26, vcc, 0x3a000, v6
	s_nop 1
	v_addc_co_u32_e32 v27, vcc, 0, v7, vcc
	v_add_co_u32_e32 v28, vcc, 0x3c000, v6
	s_nop 1
	v_addc_co_u32_e32 v29, vcc, 0, v7, vcc
	v_add_co_u32_e32 v6, vcc, s79, v6
	s_nop 1
	v_addc_co_u32_e32 v7, vcc, 0, v7, vcc
	global_load_dword v12, v[12:13], off nt
	s_nop 0
	global_load_dword v13, v[18:19], off nt
	s_nop 0
	global_load_dword v18, v[20:21], off nt
	global_load_dword v19, v[22:23], off nt
	s_nop 0
	global_load_dword v20, v[24:25], off nt
	global_load_dword v21, v[26:27], off nt
	global_load_dword v22, v[28:29], off nt
	s_nop 0
	global_load_dword v6, v[6:7], off nt
	s_waitcnt vmcnt(30)
	ds_write2_b32 v100, v2, v5 offset1:66
	s_waitcnt vmcnt(28)
	ds_write2_b32 v100, v17, v32 offset0:132 offset1:198
	v_add_u32_e32 v2, 0x400, v100
	s_waitcnt vmcnt(26)
	ds_write2_b32 v2, v33, v34 offset0:8 offset1:74
	s_waitcnt vmcnt(24)
	ds_write2_b32 v2, v35, v36 offset0:140 offset1:206
	v_add_u32_e32 v2, 0x800, v100
	s_waitcnt vmcnt(22)
	ds_write2_b32 v2, v37, v38 offset0:16 offset1:82
	s_waitcnt vmcnt(20)
	ds_write2_b32 v2, v39, v40 offset0:148 offset1:214
	v_add_u32_e32 v2, 0xc00, v100
	s_waitcnt vmcnt(18)
	ds_write2_b32 v2, v41, v42 offset0:24 offset1:90
	s_waitcnt vmcnt(16)
	ds_write2_b32 v2, v43, v44 offset0:156 offset1:222
	v_add_u32_e32 v2, 0x1000, v100
	s_waitcnt vmcnt(14)
	ds_write2_b32 v2, v45, v46 offset0:32 offset1:98
	s_waitcnt vmcnt(12)
	ds_write2_b32 v2, v47, v48 offset0:164 offset1:230
	v_add_u32_e32 v2, 0x1400, v100
	s_waitcnt vmcnt(10)
	ds_write2_b32 v2, v49, v50 offset0:40 offset1:106
	s_waitcnt vmcnt(8)
	ds_write2_b32 v2, v51, v30 offset0:172 offset1:238
	v_add_u32_e32 v2, 0x1800, v100
	s_waitcnt vmcnt(6)
	ds_write2_b32 v2, v12, v13 offset0:48 offset1:114
	s_waitcnt vmcnt(4)
	ds_write2_b32 v2, v18, v19 offset0:180 offset1:246
	v_add_u32_e32 v2, 0x1c00, v100
	s_waitcnt vmcnt(2)
	ds_write2_b32 v2, v20, v21 offset0:56 offset1:122
	s_waitcnt vmcnt(0)
	ds_write2_b32 v2, v22, v6 offset0:188 offset1:254
	s_waitcnt lgkmcnt(0)
	ds_read2_b32 v[6:7], v102 offset1:33
	s_waitcnt lgkmcnt(0)
	v_cvt_pk_bf16_f32 v18, v6, v7
	ds_read2_b32 v[6:7], v102 offset0:66 offset1:99
	s_waitcnt lgkmcnt(0)
	v_cvt_pk_bf16_f32 v19, v6, v7
	ds_read2_b32 v[6:7], v102 offset0:132 offset1:165
	v_mov_b32_e32 v5, v3
	s_waitcnt lgkmcnt(0)
	v_cvt_pk_bf16_f32 v20, v6, v7
	ds_read2_b32 v[6:7], v102 offset0:198 offset1:231
	v_lshl_add_u64 v[12:13], v[4:5], 1, v[80:81]
	v_lshlrev_b32_e32 v2, 12, v11
	s_waitcnt lgkmcnt(0)
	v_cvt_pk_bf16_f32 v21, v6, v7
	ds_read2_b32 v[6:7], v102 offset0:8 offset1:41
	v_lshl_add_u64 v[4:5], v[12:13], 0, v[2:3]
	global_store_dwordx4 v[4:5], v[18:21], off
	s_waitcnt lgkmcnt(0)
	v_cvt_pk_bf16_f32 v4, v6, v7
	ds_read2_b32 v[6:7], v102 offset0:74 offset1:107
	s_waitcnt lgkmcnt(0)
	v_cvt_pk_bf16_f32 v5, v6, v7
	ds_read2_b32 v[6:7], v102 offset0:140 offset1:173
	v_lshlrev_b32_e32 v2, 12, v10
	s_waitcnt lgkmcnt(0)
	v_cvt_pk_bf16_f32 v6, v6, v7
	ds_read2_b32 v[18:19], v102 offset0:206 offset1:239
	s_waitcnt lgkmcnt(0)
	v_cvt_pk_bf16_f32 v7, v18, v19
	v_lshl_add_u64 v[10:11], v[12:13], 0, v[2:3]
	ds_read2_b32 v[18:19], v102 offset0:16 offset1:49
	global_store_dwordx4 v[10:11], v[4:7], off
	v_lshlrev_b32_e32 v2, 12, v9
	s_waitcnt lgkmcnt(0)
	v_cvt_pk_bf16_f32 v4, v18, v19
	ds_read2_b32 v[6:7], v102 offset0:82 offset1:115
	s_waitcnt lgkmcnt(0)
	v_cvt_pk_bf16_f32 v5, v6, v7
	ds_read2_b32 v[6:7], v102 offset0:148 offset1:181
	s_waitcnt lgkmcnt(0)
	v_cvt_pk_bf16_f32 v6, v6, v7
	ds_read2_b32 v[10:11], v102 offset0:214 offset1:247
	s_waitcnt lgkmcnt(0)
	v_cvt_pk_bf16_f32 v7, v10, v11
	v_lshl_add_u64 v[18:19], v[12:13], 0, v[2:3]
	ds_read2_b32 v[10:11], v102 offset0:24 offset1:57
	global_store_dwordx4 v[18:19], v[4:7], off
	v_lshlrev_b32_e32 v2, 12, v8
	v_lshl_add_u64 v[8:9], v[12:13], 0, v[2:3]
	s_waitcnt lgkmcnt(0)
	v_cvt_pk_bf16_f32 v4, v10, v11
	ds_read2_b32 v[6:7], v102 offset0:90 offset1:123
	s_waitcnt lgkmcnt(0)
	v_cvt_pk_bf16_f32 v5, v6, v7
	ds_read2_b32 v[6:7], v102 offset0:156 offset1:189
	s_waitcnt lgkmcnt(0)
	v_cvt_pk_bf16_f32 v6, v6, v7
	ds_read2_b32 v[10:11], v102 offset0:222 offset1:255
	s_waitcnt lgkmcnt(0)
	v_cvt_pk_bf16_f32 v7, v10, v11
	global_store_dwordx4 v[8:9], v[4:7], off
	s_waitcnt lgkmcnt(0)

.LBB0_28:
	s_andn2_saveexec_b64 s[62:63], s[62:63]
	s_cbranch_execz .LBB0_33
	v_add_u32_e32 v2, 0xffffbe00, v16
	v_lshrrev_b32_e32 v2, 1, v2
	v_and_b32_e32 v52, 0x7fffffc0, v2
	v_or_b32_e32 v2, v52, v73
	v_and_b32_e32 v12, 0xfe0, v14
	v_lshlrev_b64 v[4:5], 14, v[2:3]
	s_waitcnt lgkmcnt(0)
	v_lshl_add_u64 v[4:5], s[56:57], 0, v[4:5]
	v_lshlrev_b32_e32 v2, 2, v12
	v_lshl_add_u64 v[4:5], v[4:5], 0, v[2:3]
	v_lshlrev_b32_e32 v2, 2, v70
	v_lshl_add_u64 v[4:5], v[4:5], 0, v[2:3]
	v_add_co_u32_e32 v6, vcc, s80, v4
	s_mov_b32 s3, 0x40000
	s_nop 0
	v_addc_co_u32_e32 v7, vcc, 0, v5, vcc
	v_add_co_u32_e32 v8, vcc, s81, v4
	v_mov_b32_e32 v2, v52
	s_nop 0
	v_addc_co_u32_e32 v9, vcc, 0, v5, vcc
	v_add_co_u32_e32 v10, vcc, s83, v4
	s_nop 1
	v_addc_co_u32_e32 v11, vcc, 0, v5, vcc
	v_add_co_u32_e32 v22, vcc, s75, v4
	s_nop 1
	v_addc_co_u32_e32 v23, vcc, 0, v5, vcc
	v_add_co_u32_e32 v24, vcc, s84, v4
	s_nop 1
	v_addc_co_u32_e32 v25, vcc, 0, v5, vcc
	v_add_co_u32_e32 v26, vcc, s86, v4
	s_nop 1
	v_addc_co_u32_e32 v27, vcc, 0, v5, vcc
	v_add_co_u32_e32 v28, vcc, s87, v4
	s_nop 1
	v_addc_co_u32_e32 v29, vcc, 0, v5, vcc
	global_load_dword v13, v[4:5], off nt
	global_load_dword v17, v[6:7], off nt
	global_load_dword v18, v[8:9], off nt
	global_load_dword v20, v[10:11], off nt
	global_load_dword v19, v[22:23], off nt
	global_load_dword v21, v[24:25], off nt
	s_nop 0
	global_load_dword v22, v[26:27], off nt
	global_load_dword v23, v[28:29], off nt
	v_add_co_u32_e32 v6, vcc, s3, v4
	s_mov_b32 s3, 0x48000
	s_nop 0
	v_addc_co_u32_e32 v7, vcc, 0, v5, vcc
	v_add_co_u32_e32 v8, vcc, s3, v4
	s_mov_b32 s3, 0x50000
	s_nop 0
	v_addc_co_u32_e32 v9, vcc, 0, v5, vcc
	v_add_co_u32_e32 v10, vcc, s3, v4
	s_mov_b32 s3, 0x60000
	s_nop 0
	v_addc_co_u32_e32 v11, vcc, 0, v5, vcc
	v_add_co_u32_e32 v28, vcc, s88, v4
	s_nop 1
	v_addc_co_u32_e32 v29, vcc, 0, v5, vcc
	v_add_co_u32_e32 v30, vcc, s3, v4
	s_mov_b32 s3, 0x68000
	s_nop 0
	v_addc_co_u32_e32 v31, vcc, 0, v5, vcc
	v_add_co_u32_e32 v32, vcc, s3, v4
	s_mov_b32 s3, 0x70000
	s_nop 0
	v_addc_co_u32_e32 v33, vcc, 0, v5, vcc
	v_add_co_u32_e32 v34, vcc, s3, v4
	s_mov_b32 s3, 0x78000
	s_nop 0
	v_addc_co_u32_e32 v35, vcc, 0, v5, vcc
	v_add_co_u32_e32 v36, vcc, s3, v4
	s_mov_b32 s3, 0x80000
	s_nop 0
	v_addc_co_u32_e32 v37, vcc, 0, v5, vcc
	global_load_dword v24, v[6:7], off nt
	global_load_dword v25, v[8:9], off nt
	global_load_dword v26, v[10:11], off nt
	s_nop 0
	global_load_dword v28, v[28:29], off nt
	s_nop 0
	global_load_dword v27, v[30:31], off nt
	global_load_dword v29, v[32:33], off nt
	s_nop 0
	global_load_dword v30, v[34:35], off nt
	global_load_dword v31, v[36:37], off nt
	v_add_co_u32_e32 v6, vcc, s3, v4
	s_mov_b32 s3, 0x88000
	s_nop 0
	v_addc_co_u32_e32 v7, vcc, 0, v5, vcc
	v_add_co_u32_e32 v8, vcc, s3, v4
	s_mov_b32 s3, 0x90000
	s_nop 0
	v_addc_co_u32_e32 v9, vcc, 0, v5, vcc
	v_add_co_u32_e32 v10, vcc, s3, v4
	s_mov_b32 s3, 0x98000
	s_nop 0
	v_addc_co_u32_e32 v11, vcc, 0, v5, vcc
	v_add_co_u32_e32 v36, vcc, s3, v4
	s_mov_b32 s3, 0xa0000
	s_nop 0
	v_addc_co_u32_e32 v37, vcc, 0, v5, vcc
	v_add_co_u32_e32 v38, vcc, s3, v4
	s_mov_b32 s3, 0xa8000
	s_nop 0
	v_addc_co_u32_e32 v39, vcc, 0, v5, vcc
	v_add_co_u32_e32 v40, vcc, s3, v4
	s_mov_b32 s3, 0xb8000
	s_nop 0
	v_addc_co_u32_e32 v41, vcc, 0, v5, vcc
	v_add_co_u32_e32 v42, vcc, s89, v4
	s_nop 1
	v_addc_co_u32_e32 v43, vcc, 0, v5, vcc
	v_add_co_u32_e32 v44, vcc, s3, v4
	s_mov_b32 s3, 0xc0000
	s_nop 0
	v_addc_co_u32_e32 v45, vcc, 0, v5, vcc
	global_load_dword v32, v[6:7], off nt
	global_load_dword v33, v[8:9], off nt
	global_load_dword v34, v[10:11], off nt
	s_nop 0
	global_load_dword v36, v[36:37], off nt
	s_nop 0
	global_load_dword v35, v[38:39], off nt
	global_load_dword v37, v[40:41], off nt
	s_nop 0
	global_load_dword v38, v[42:43], off nt
	global_load_dword v39, v[44:45], off nt
	v_add_co_u32_e32 v6, vcc, s3, v4
	s_mov_b32 s3, 0xc8000
	s_nop 0
	v_addc_co_u32_e32 v7, vcc, 0, v5, vcc
	v_add_co_u32_e32 v8, vcc, s3, v4
	s_mov_b32 s3, 0xd0000
	s_nop 0
	v_addc_co_u32_e32 v9, vcc, 0, v5, vcc
	v_add_co_u32_e32 v10, vcc, s3, v4
	s_mov_b32 s3, 0xd8000
	s_nop 0
	v_addc_co_u32_e32 v11, vcc, 0, v5, vcc
	v_add_co_u32_e32 v44, vcc, s3, v4
	s_mov_b32 s3, 0xe0000
	s_nop 0
	v_addc_co_u32_e32 v45, vcc, 0, v5, vcc
	v_add_co_u32_e32 v46, vcc, s3, v4
	s_nop 1
	v_addc_co_u32_e32 v47, vcc, 0, v5, vcc
	v_add_co_u32_e32 v48, vcc, 0xe8000, v4
	s_nop 1
	v_addc_co_u32_e32 v49, vcc, 0, v5, vcc
	v_add_co_u32_e32 v50, vcc, 0xf0000, v4
	s_nop 1
	v_addc_co_u32_e32 v51, vcc, 0, v5, vcc
	v_add_co_u32_e32 v4, vcc, 0xf8000, v4
	s_nop 1
	v_addc_co_u32_e32 v5, vcc, 0, v5, vcc
	global_load_dword v40, v[6:7], off nt
	global_load_dword v41, v[8:9], off nt
	global_load_dword v42, v[10:11], off nt
	s_nop 0
	global_load_dword v44, v[44:45], off nt
	s_nop 0
	global_load_dword v43, v[46:47], off nt
	global_load_dword v45, v[48:49], off nt
	s_nop 0
	global_load_dword v46, v[50:51], off nt
	global_load_dword v47, v[4:5], off nt
	s_andn2_b64 vcc, exec, s[22:23]
	s_cbranch_vccnz .LBB0_31
	v_lshl_add_u64 v[8:9], v[2:3], 2, v[74:75]
	global_load_dwordx4 v[4:7], v[8:9], off offset:16
	s_nop 0
	global_load_dwordx4 v[8:11], v[8:9], off
	s_branch .LBB0_32

.LBB0_34:
	s_andn2_saveexec_b64 s[60:61], s[60:61]
	s_cbranch_execz .LBB0_36
	v_add_u32_e32 v2, 0xffffd400, v16
	v_mul_u32_u24_e32 v2, 0xba2f, v2
	v_lshrrev_b32_e32 v7, 26, v2
	v_mul_u32_u24_e32 v2, 0xfa80, v7
	v_add_u32_e32 v2, v2, v16
	v_add_u16_e32 v2, 0xd400, v2
	v_ashrrev_i16_e32 v4, 15, v2
	v_lshrrev_b16_e32 v4, 11, v4
	v_add_u16_e32 v4, v2, v4
	v_ashrrev_i16_e32 v6, 5, v4
	v_lshlrev_b32_sdwa v6, v110, sext(v6) dst_sel:DWORD dst_unused:UNUSED_PAD src0_sel:DWORD src1_sel:WORD_0
	v_and_b32_e32 v4, 0xffffffe0, v4
	v_or_b32_e32 v10, v6, v73
	v_sub_u16_e32 v2, v2, v4
	v_mov_b64_e32 v[4:5], s[20:21]
	v_ashrrev_i32_e32 v11, 31, v10
	v_mad_u64_u32 v[8:9], s[62:63], v7, s90, v[4:5]
	v_lshlrev_b32_sdwa v4, v109, sext(v2) dst_sel:DWORD dst_unused:UNUSED_PAD src0_sel:DWORD src1_sel:WORD_0
	v_lshlrev_b64 v[10:11], 12, v[10:11]
	v_lshl_add_u64 v[8:9], v[8:9], 0, v[10:11]
	v_ashrrev_i32_e32 v5, 31, v4
	v_lshl_add_u64 v[8:9], v[4:5], 2, v[8:9]
	v_lshlrev_b32_e32 v2, 2, v70
	v_lshl_add_u64 v[8:9], v[8:9], 0, v[2:3]
	v_add_co_u32_e32 v10, vcc, s76, v8
	s_movk_i32 s3, 0x4000
	s_nop 0
	v_addc_co_u32_e32 v11, vcc, 0, v9, vcc
	v_add_co_u32_e32 v12, vcc, s3, v8
	s_movk_i32 s3, 0x6000
	s_nop 0
	v_addc_co_u32_e32 v13, vcc, 0, v9, vcc
	v_add_co_u32_e32 v18, vcc, s3, v8
	s_mov_b32 s3, 0xa000
	s_nop 0
	v_addc_co_u32_e32 v19, vcc, 0, v9, vcc
	v_add_co_u32_e32 v20, vcc, s80, v8
	s_nop 1
	v_addc_co_u32_e32 v21, vcc, 0, v9, vcc
	v_add_co_u32_e32 v22, vcc, s3, v8
	s_mov_b32 s3, 0xc000
	s_nop 0
	v_addc_co_u32_e32 v23, vcc, 0, v9, vcc
	v_add_co_u32_e32 v24, vcc, s3, v8
	s_mov_b32 s3, 0xe000
	s_nop 0
	v_addc_co_u32_e32 v25, vcc, 0, v9, vcc
	v_add_co_u32_e32 v26, vcc, s3, v8
	s_mov_b32 s3, 0x12000
	s_nop 0
	v_addc_co_u32_e32 v27, vcc, 0, v9, vcc
	global_load_dword v2, v[8:9], off nt
	global_load_dword v5, v[10:11], off nt
	global_load_dword v17, v[12:13], off nt
	global_load_dword v30, v[18:19], off nt
	global_load_dword v31, v[20:21], off nt
	global_load_dword v32, v[22:23], off nt
	global_load_dword v33, v[24:25], off nt
	global_load_dword v34, v[26:27], off nt
	v_add_co_u32_e32 v10, vcc, s81, v8
	s_nop 1
	v_addc_co_u32_e32 v11, vcc, 0, v9, vcc
	v_add_co_u32_e32 v12, vcc, s3, v8
	s_mov_b32 s3, 0x14000
	s_nop 0
	v_addc_co_u32_e32 v13, vcc, 0, v9, vcc
	v_add_co_u32_e32 v18, vcc, s3, v8
	s_mov_b32 s3, 0x1a000
	s_nop 0
	v_addc_co_u32_e32 v19, vcc, 0, v9, vcc
	v_add_co_u32_e32 v20, vcc, s82, v8
	s_nop 1
	v_addc_co_u32_e32 v21, vcc, 0, v9, vcc
	v_add_co_u32_e32 v22, vcc, s83, v8
	s_nop 1
	v_addc_co_u32_e32 v23, vcc, 0, v9, vcc
	v_add_co_u32_e32 v24, vcc, s3, v8
	s_mov_b32 s3, 0x1c000
	s_nop 0
	v_addc_co_u32_e32 v25, vcc, 0, v9, vcc
	v_add_co_u32_e32 v26, vcc, s3, v8
	s_mov_b32 s3, 0x1e000
	s_nop 0
	v_addc_co_u32_e32 v27, vcc, 0, v9, vcc
	v_add_co_u32_e32 v28, vcc, s3, v8
	s_mov_b32 s3, 0x22000
	s_nop 0
	v_addc_co_u32_e32 v29, vcc, 0, v9, vcc
	global_load_dword v35, v[10:11], off nt
	global_load_dword v36, v[12:13], off nt
	global_load_dword v37, v[18:19], off nt
	global_load_dword v38, v[20:21], off nt
	global_load_dword v39, v[22:23], off nt
	global_load_dword v40, v[24:25], off nt
	global_load_dword v41, v[26:27], off nt
	global_load_dword v42, v[28:29], off nt
	v_add_co_u32_e32 v10, vcc, s75, v8
	s_nop 1
	v_addc_co_u32_e32 v11, vcc, 0, v9, vcc
	v_add_co_u32_e32 v12, vcc, s3, v8
	s_mov_b32 s3, 0x24000
	s_nop 0
	v_addc_co_u32_e32 v13, vcc, 0, v9, vcc
	v_add_co_u32_e32 v18, vcc, s3, v8
	s_mov_b32 s3, 0x26000
	s_nop 0
	v_addc_co_u32_e32 v19, vcc, 0, v9, vcc
	v_add_co_u32_e32 v20, vcc, s3, v8
	s_mov_b32 s3, 0x2a000
	s_nop 0
	v_addc_co_u32_e32 v21, vcc, 0, v9, vcc
	v_add_co_u32_e32 v22, vcc, s84, v8
	s_nop 1
	v_addc_co_u32_e32 v23, vcc, 0, v9, vcc
	v_add_co_u32_e32 v24, vcc, s3, v8
	s_mov_b32 s3, 0x2e000
	s_nop 0
	v_addc_co_u32_e32 v25, vcc, 0, v9, vcc
	v_add_co_u32_e32 v26, vcc, s85, v8
	s_nop 1
	v_addc_co_u32_e32 v27, vcc, 0, v9, vcc
	v_add_co_u32_e32 v28, vcc, s3, v8
	s_mov_b32 s3, 0x32000
	s_nop 0
	v_addc_co_u32_e32 v29, vcc, 0, v9, vcc
	global_load_dword v43, v[10:11], off nt
	global_load_dword v44, v[12:13], off nt
	global_load_dword v45, v[18:19], off nt
	global_load_dword v46, v[20:21], off nt
	global_load_dword v47, v[22:23], off nt
	global_load_dword v48, v[24:25], off nt
	global_load_dword v49, v[26:27], off nt
	s_nop 0
	global_load_dword v28, v[28:29], off nt
	v_add_co_u32_e32 v10, vcc, s86, v8
	s_nop 1
	v_addc_co_u32_e32 v11, vcc, 0, v9, vcc
	v_add_co_u32_e32 v12, vcc, s3, v8
	s_mov_b32 s3, 0x34000
	s_nop 0
	v_addc_co_u32_e32 v13, vcc, 0, v9, vcc
	v_add_co_u32_e32 v18, vcc, s3, v8
	s_mov_b32 s3, 0x36000
	s_nop 0
	v_addc_co_u32_e32 v19, vcc, 0, v9, vcc
	v_add_co_u32_e32 v20, vcc, s3, v8
	s_mov_b32 s3, 0x3a000
	s_nop 0
	v_addc_co_u32_e32 v21, vcc, 0, v9, vcc
	v_add_co_u32_e32 v22, vcc, s87, v8
	s_nop 1
	v_addc_co_u32_e32 v23, vcc, 0, v9, vcc
	v_add_co_u32_e32 v24, vcc, s3, v8
	s_mov_b32 s3, 0x3c000
	s_nop 0
	v_addc_co_u32_e32 v25, vcc, 0, v9, vcc
	v_add_co_u32_e32 v26, vcc, s3, v8
	s_mov_b32 s3, 0x580000
	s_nop 0
	v_addc_co_u32_e32 v27, vcc, 0, v9, vcc
	v_add_co_u32_e32 v8, vcc, s79, v8
	s_nop 1
	v_addc_co_u32_e32 v9, vcc, 0, v9, vcc
	global_load_dword v10, v[10:11], off nt
	s_nop 0
	global_load_dword v11, v[12:13], off nt
	s_nop 0
	global_load_dword v12, v[18:19], off nt
	global_load_dword v13, v[20:21], off nt
	s_nop 0
	global_load_dword v18, v[22:23], off nt
	global_load_dword v19, v[24:25], off nt
	global_load_dword v20, v[26:27], off nt
	s_nop 0
	global_load_dword v8, v[8:9], off nt
	s_waitcnt vmcnt(30)
	ds_write2_b32 v100, v2, v5 offset1:66
	s_waitcnt vmcnt(28)
	ds_write2_b32 v100, v17, v30 offset0:132 offset1:198
	v_add_u32_e32 v2, 0x400, v100
	s_waitcnt vmcnt(26)
	ds_write2_b32 v2, v31, v32 offset0:8 offset1:74
	s_waitcnt vmcnt(24)
	ds_write2_b32 v2, v33, v34 offset0:140 offset1:206
	v_add_u32_e32 v2, 0x800, v100
	s_waitcnt vmcnt(22)
	ds_write2_b32 v2, v35, v36 offset0:16 offset1:82
	s_waitcnt vmcnt(20)
	ds_write2_b32 v2, v37, v38 offset0:148 offset1:214
	v_add_u32_e32 v2, 0xc00, v100
	s_waitcnt vmcnt(18)
	ds_write2_b32 v2, v39, v40 offset0:24 offset1:90
	s_waitcnt vmcnt(16)
	ds_write2_b32 v2, v41, v42 offset0:156 offset1:222
	v_add_u32_e32 v2, 0x1000, v100
	s_waitcnt vmcnt(14)
	ds_write2_b32 v2, v43, v44 offset0:32 offset1:98
	s_waitcnt vmcnt(12)
	ds_write2_b32 v2, v45, v46 offset0:164 offset1:230
	v_add_u32_e32 v2, 0x1400, v100
	s_waitcnt vmcnt(10)
	ds_write2_b32 v2, v47, v48 offset0:40 offset1:106
	s_waitcnt vmcnt(8)
	ds_write2_b32 v2, v49, v28 offset0:172 offset1:238
	v_add_u32_e32 v2, 0x1800, v100
	s_waitcnt vmcnt(6)
	ds_write2_b32 v2, v10, v11 offset0:48 offset1:114
	s_waitcnt vmcnt(4)
	ds_write2_b32 v2, v12, v13 offset0:180 offset1:246
	v_add_u32_e32 v2, 0x1c00, v100
	s_waitcnt vmcnt(2)
	ds_write2_b32 v2, v18, v19 offset0:56 offset1:122
	s_waitcnt vmcnt(0)
	ds_write2_b32 v2, v20, v8 offset0:188 offset1:254
	s_waitcnt lgkmcnt(0)
	ds_read2_b32 v[8:9], v102 offset1:33
	v_mov_b64_e32 v[12:13], s[50:51]
	s_waitcnt lgkmcnt(0)
	v_cvt_pk_bf16_f32 v8, v8, v9
	ds_read2_b32 v[10:11], v102 offset0:66 offset1:99
	v_mad_u64_u32 v[12:13], s[62:63], v7, s3, v[12:13]
	v_ashrrev_i32_e32 v7, 31, v6
	s_waitcnt lgkmcnt(0)
	v_cvt_pk_bf16_f32 v9, v10, v11
	ds_read2_b32 v[10:11], v102 offset0:132 offset1:165
	v_lshl_add_u64 v[6:7], v[6:7], 1, v[12:13]
	v_lshlrev_b32_e32 v2, 1, v72
	s_waitcnt lgkmcnt(0)
	v_cvt_pk_bf16_f32 v10, v10, v11
	ds_read2_b32 v[18:19], v102 offset0:198 offset1:231
	v_lshl_add_u64 v[12:13], v[6:7], 0, v[2:3]
	v_or_b32_e32 v2, v4, v101
	s_waitcnt lgkmcnt(0)
	v_cvt_pk_bf16_f32 v11, v18, v19
	v_mul_i32_i24_e32 v18, 0xb00, v2
	v_ashrrev_i32_e32 v19, 31, v18
	ds_read2_b32 v[6:7], v102 offset0:8 offset1:41
	v_lshl_add_u64 v[18:19], v[18:19], 1, v[12:13]
	v_or_b32_e32 v2, v4, v103
	global_store_dwordx4 v[18:19], v[8:11], off
	s_waitcnt lgkmcnt(0)
	v_cvt_pk_bf16_f32 v6, v6, v7
	ds_read2_b32 v[8:9], v102 offset0:74 offset1:107
	v_mul_i32_i24_e32 v18, 0xb00, v2
	s_waitcnt lgkmcnt(0)
	v_cvt_pk_bf16_f32 v7, v8, v9
	ds_read2_b32 v[8:9], v102 offset0:140 offset1:173
	v_ashrrev_i32_e32 v19, 31, v18
	s_waitcnt lgkmcnt(0)
	v_cvt_pk_bf16_f32 v8, v8, v9
	ds_read2_b32 v[10:11], v102 offset0:206 offset1:239
	s_waitcnt lgkmcnt(0)
	v_cvt_pk_bf16_f32 v9, v10, v11
	v_lshl_add_u64 v[18:19], v[18:19], 1, v[12:13]
	v_or_b32_e32 v2, v4, v104
	ds_read2_b32 v[10:11], v102 offset0:16 offset1:49
	global_store_dwordx4 v[18:19], v[6:9], off
	v_mul_i32_i24_e32 v18, 0xb00, v2
	v_ashrrev_i32_e32 v19, 31, v18
	s_waitcnt lgkmcnt(0)
	v_cvt_pk_bf16_f32 v6, v10, v11
	ds_read2_b32 v[8:9], v102 offset0:82 offset1:115
	s_waitcnt lgkmcnt(0)
	v_cvt_pk_bf16_f32 v7, v8, v9
	ds_read2_b32 v[8:9], v102 offset0:148 offset1:181
	v_or_b32_e32 v2, v4, v105
	s_waitcnt lgkmcnt(0)
	v_cvt_pk_bf16_f32 v8, v8, v9
	ds_read2_b32 v[10:11], v102 offset0:214 offset1:247
	s_waitcnt lgkmcnt(0)
	v_cvt_pk_bf16_f32 v9, v10, v11
	v_lshl_add_u64 v[18:19], v[18:19], 1, v[12:13]
	v_mul_i32_i24_e32 v4, 0xb00, v2
	ds_read2_b32 v[10:11], v102 offset0:24 offset1:57
	global_store_dwordx4 v[18:19], v[6:9], off
	v_ashrrev_i32_e32 v5, 31, v4
	v_lshl_add_u64 v[4:5], v[4:5], 1, v[12:13]
	s_waitcnt lgkmcnt(0)
	v_cvt_pk_bf16_f32 v6, v10, v11
	ds_read2_b32 v[8:9], v102 offset0:90 offset1:123
	s_waitcnt lgkmcnt(0)
	v_cvt_pk_bf16_f32 v7, v8, v9
	ds_read2_b32 v[8:9], v102 offset0:156 offset1:189
	s_waitcnt lgkmcnt(0)
	v_cvt_pk_bf16_f32 v8, v8, v9
	ds_read2_b32 v[10:11], v102 offset0:222 offset1:255
	s_waitcnt lgkmcnt(0)
	v_cvt_pk_bf16_f32 v9, v10, v11
	global_store_dwordx4 v[4:5], v[6:9], off
	s_waitcnt lgkmcnt(0)

.LBB0_37:
	s_andn2_saveexec_b64 s[30:31], s[30:31]
	s_cbranch_execz .LBB0_19
	v_mul_hi_i32 v2, v16, s91
	v_lshrrev_b32_e32 v4, 31, v2
	v_ashrrev_i32_e32 v2, 9, v2
	v_add_u32_e32 v18, v2, v4
	v_mul_i32_i24_e32 v2, 0xfffff500, v18
	v_add_u32_e32 v2, v2, v16
	v_mul_hi_i32 v4, v2, s91
	v_lshrrev_b32_e32 v5, 31, v4
	v_ashrrev_i32_e32 v4, 5, v4
	v_add_u32_e32 v5, v4, v5
	s_movk_i32 s3, 0xb0
	v_mul_lo_u32 v4, v5, s3
	v_sub_u32_e32 v2, v2, v4
	v_lshlrev_b32_e32 v17, 5, v2
	v_bfe_i32 v4, v2, 2, 1
	v_lshlrev_b32_e32 v2, 4, v2
	v_and_b32_e32 v4, 0xb00, v4
	v_and_b32_e32 v2, 0xffffff80, v2
	v_add_u32_e32 v2, v4, v2
	s_movk_i32 s3, 0x60
	v_and_or_b32 v4, v17, s3, v2
	v_mov_b64_e32 v[6:7], s[18:19]
	s_mov_b32 s3, 0x1600000
	v_lshlrev_b32_e32 v12, 6, v5
	v_mad_i64_i32 v[6:7], s[60:61], v18, s3, v[6:7]
	v_or_b32_e32 v2, v12, v73
	s_movk_i32 s3, 0x5800
	v_mad_i64_i32 v[6:7], s[60:61], v2, s3, v[6:7]
	v_ashrrev_i32_e32 v5, 31, v4
	v_lshl_add_u64 v[4:5], v[4:5], 2, v[6:7]
	v_lshlrev_b32_e32 v2, 2, v70
	v_lshl_add_u64 v[4:5], v[4:5], 0, v[2:3]
	s_mov_b32 s3, 0xb000
	v_add_co_u32_e32 v6, vcc, s3, v4
	s_mov_b32 s3, 0x21000
	s_nop 0
	v_addc_co_u32_e32 v7, vcc, 0, v5, vcc
	v_add_co_u32_e32 v8, vcc, s82, v4
	v_ashrrev_i32_e32 v13, 31, v12
	s_nop 0
	v_addc_co_u32_e32 v9, vcc, 0, v5, vcc
	v_add_co_u32_e32 v10, vcc, s3, v4
	s_mov_b32 s3, 0x37000
	s_nop 0
	v_addc_co_u32_e32 v11, vcc, 0, v5, vcc
	v_add_co_u32_e32 v24, vcc, s85, v4
	s_nop 1
	v_addc_co_u32_e32 v25, vcc, 0, v5, vcc
	v_add_co_u32_e32 v26, vcc, s3, v4
	s_mov_b32 s3, 0x42000
	s_nop 0
	v_addc_co_u32_e32 v27, vcc, 0, v5, vcc
	v_add_co_u32_e32 v28, vcc, s3, v4
	s_mov_b32 s3, 0x4d000
	s_nop 0
	v_addc_co_u32_e32 v29, vcc, 0, v5, vcc
	v_add_co_u32_e32 v30, vcc, s3, v4
	s_mov_b32 s3, 0x63000
	s_nop 0
	v_addc_co_u32_e32 v31, vcc, 0, v5, vcc
	global_load_dword v19, v[4:5], off nt
	global_load_dword v20, v[6:7], off nt
	global_load_dword v21, v[8:9], off nt
	global_load_dword v23, v[10:11], off nt
	global_load_dword v22, v[24:25], off nt
	s_nop 0
	global_load_dword v24, v[26:27], off nt
	global_load_dword v25, v[28:29], off nt
	s_nop 0
	global_load_dword v26, v[30:31], off nt
	v_add_co_u32_e32 v6, vcc, s88, v4
	s_nop 1
	v_addc_co_u32_e32 v7, vcc, 0, v5, vcc
	v_add_co_u32_e32 v8, vcc, s3, v4
	s_mov_b32 s3, 0x6e000
	s_nop 0
	v_addc_co_u32_e32 v9, vcc, 0, v5, vcc
	v_add_co_u32_e32 v10, vcc, s3, v4
	s_mov_b32 s3, 0x79000
	s_nop 0
	v_addc_co_u32_e32 v11, vcc, 0, v5, vcc
	v_add_co_u32_e32 v30, vcc, s3, v4
	s_mov_b32 s3, 0x84000
	s_nop 0
	v_addc_co_u32_e32 v31, vcc, 0, v5, vcc
	v_add_co_u32_e32 v32, vcc, s3, v4
	s_mov_b32 s3, 0x8f000
	s_nop 0
	v_addc_co_u32_e32 v33, vcc, 0, v5, vcc
	v_add_co_u32_e32 v34, vcc, s3, v4
	s_mov_b32 s3, 0x9a000
	s_nop 0
	v_addc_co_u32_e32 v35, vcc, 0, v5, vcc
	v_add_co_u32_e32 v36, vcc, s3, v4
	s_mov_b32 s3, 0xa5000
	s_nop 0
	v_addc_co_u32_e32 v37, vcc, 0, v5, vcc
	v_add_co_u32_e32 v38, vcc, s3, v4
	s_mov_b32 s3, 0xbb000
	s_nop 0
	v_addc_co_u32_e32 v39, vcc, 0, v5, vcc
	global_load_dword v27, v[6:7], off nt
	global_load_dword v28, v[8:9], off nt
	global_load_dword v29, v[10:11], off nt
	s_nop 0
	global_load_dword v31, v[30:31], off nt
	s_nop 0
	global_load_dword v30, v[32:33], off nt
	s_nop 0
	global_load_dword v32, v[34:35], off nt
	global_load_dword v33, v[36:37], off nt
	s_nop 0
	global_load_dword v34, v[38:39], off nt
	v_add_co_u32_e32 v6, vcc, s89, v4
	s_nop 1
	v_addc_co_u32_e32 v7, vcc, 0, v5, vcc
	v_add_co_u32_e32 v8, vcc, s3, v4
	s_mov_b32 s3, 0xc6000
	s_nop 0
	v_addc_co_u32_e32 v9, vcc, 0, v5, vcc
	v_add_co_u32_e32 v10, vcc, s3, v4
	s_mov_b32 s3, 0xd1000
	s_nop 0
	v_addc_co_u32_e32 v11, vcc, 0, v5, vcc
	v_add_co_u32_e32 v38, vcc, s3, v4
	s_mov_b32 s3, 0xdc000
	s_nop 0
	v_addc_co_u32_e32 v39, vcc, 0, v5, vcc
	v_add_co_u32_e32 v40, vcc, s3, v4
	s_mov_b32 s3, 0xe7000
	s_nop 0
	v_addc_co_u32_e32 v41, vcc, 0, v5, vcc
	v_add_co_u32_e32 v42, vcc, s3, v4
	s_mov_b32 s3, 0xf2000
	s_nop 0
	v_addc_co_u32_e32 v43, vcc, 0, v5, vcc
	v_add_co_u32_e32 v44, vcc, s3, v4
	s_mov_b32 s3, 0xfd000
	s_nop 0
	v_addc_co_u32_e32 v45, vcc, 0, v5, vcc
	v_add_co_u32_e32 v46, vcc, s3, v4
	s_mov_b32 s3, 0x108000
	s_nop 0
	v_addc_co_u32_e32 v47, vcc, 0, v5, vcc
	global_load_dword v35, v[6:7], off nt
	global_load_dword v36, v[8:9], off nt
	global_load_dword v37, v[10:11], off nt
	s_nop 0
	global_load_dword v39, v[38:39], off nt
	s_nop 0
	global_load_dword v38, v[40:41], off nt
	s_nop 0
	global_load_dword v40, v[42:43], off nt
	global_load_dword v41, v[44:45], off nt
	s_nop 0
	global_load_dword v42, v[46:47], off nt
	v_add_co_u32_e32 v6, vcc, s3, v4
	s_mov_b32 s3, 0x113000
	s_nop 0
	v_addc_co_u32_e32 v7, vcc, 0, v5, vcc
	v_add_co_u32_e32 v8, vcc, s3, v4
	s_mov_b32 s3, 0x11e000
	s_nop 0
	v_addc_co_u32_e32 v9, vcc, 0, v5, vcc
	v_add_co_u32_e32 v10, vcc, s3, v4
	s_mov_b32 s3, 0x129000
	s_nop 0
	v_addc_co_u32_e32 v11, vcc, 0, v5, vcc
	v_add_co_u32_e32 v46, vcc, s3, v4
	s_mov_b32 s3, 0x134000
	s_nop 0
	v_addc_co_u32_e32 v47, vcc, 0, v5, vcc
	v_add_co_u32_e32 v48, vcc, s3, v4
	s_nop 1
	v_addc_co_u32_e32 v49, vcc, 0, v5, vcc
	v_add_co_u32_e32 v50, vcc, 0x13f000, v4
	s_nop 1
	v_addc_co_u32_e32 v51, vcc, 0, v5, vcc
	v_add_co_u32_e32 v52, vcc, 0x14a000, v4
	s_nop 1
	v_addc_co_u32_e32 v53, vcc, 0, v5, vcc
	v_add_co_u32_e32 v4, vcc, 0x155000, v4
	s_nop 1
	v_addc_co_u32_e32 v5, vcc, 0, v5, vcc
	global_load_dword v43, v[6:7], off nt
	global_load_dword v44, v[8:9], off nt
	global_load_dword v45, v[10:11], off nt
	s_nop 0
	global_load_dword v47, v[46:47], off nt
	s_nop 0
	global_load_dword v46, v[48:49], off nt
	s_nop 0
	global_load_dword v48, v[50:51], off nt
	global_load_dword v49, v[52:53], off nt
	s_nop 0
	global_load_dword v50, v[4:5], off nt
	s_and_b64 vcc, exec, s[54:55]
	s_cbranch_vccz .LBB0_40
	v_lshlrev_b32_e32 v4, 10, v18
	v_ashrrev_i32_e32 v5, 31, v4
	v_lshl_add_u64 v[4:5], v[4:5], 2, s[16:17]
	v_lshl_add_u64 v[4:5], v[12:13], 2, v[4:5]
	v_lshlrev_b32_e32 v2, 2, v72
	v_lshl_add_u64 v[8:9], v[4:5], 0, v[2:3]
	global_load_dwordx4 v[4:7], v[8:9], off offset:16
	s_nop 0
	global_load_dwordx4 v[8:11], v[8:9], off
	s_cbranch_execnz .LBB0_18
	s_branch .LBB0_41

.LBB0_45:
	global_load_dwordx4 v[10:13], v[92:93], off offset:-3072 nt
	global_load_dwordx4 v[6:9], v[92:93], off offset:-2048 nt
	global_load_dwordx4 v[22:25], v[92:93], off offset:-4096 nt
	v_add_co_u32_e32 v4, vcc, 0xffffd000, v92
	s_mov_b32 s3, 0x6000000
	s_nop 0
	v_addc_co_u32_e32 v5, vcc, -1, v93, vcc
	global_load_dwordx4 v[66:69], v[4:5], off offset:-3072 nt
	global_load_dwordx4 v[62:65], v[4:5], off offset:-2048 nt
	global_load_dwordx4 v[58:61], v[4:5], off offset:-1024 nt
	global_load_dwordx4 v[54:57], v[4:5], off nt
	v_add_co_u32_e32 v4, vcc, 0xffffe000, v92
	s_waitcnt vmcnt(6)
	v_mul_f32_e32 v2, v11, v11
	v_addc_co_u32_e32 v5, vcc, -1, v93, vcc
	global_load_dwordx4 v[50:53], v[4:5], off offset:-3072 nt
	global_load_dwordx4 v[46:49], v[4:5], off offset:-2048 nt
	global_load_dwordx4 v[42:45], v[4:5], off offset:-1024 nt
	global_load_dwordx4 v[38:41], v[4:5], off nt
	v_add_co_u32_e32 v4, vcc, 0xfffff000, v92
	s_waitcnt vmcnt(8)
	v_mul_f32_e32 v98, v23, v23
	v_addc_co_u32_e32 v5, vcc, -1, v93, vcc
	global_load_dwordx4 v[34:37], v[4:5], off offset:-3072 nt
	global_load_dwordx4 v[30:33], v[4:5], off offset:-2048 nt
	global_load_dwordx4 v[26:29], v[4:5], off offset:-1024 nt
	global_load_dwordx4 v[18:21], v[92:93], off offset:-1024 nt
	global_load_dwordx4 v[14:17], v[92:93], off nt
	v_mul_f32_e32 v4, v13, v13
	v_mul_f32_e32 v99, v25, v25
	v_fmac_f32_e32 v2, v10, v10
	v_fmac_f32_e32 v4, v12, v12
	v_fmac_f32_e32 v98, v22, v22
	v_fmac_f32_e32 v99, v24, v24
	v_add_f32_e32 v118, v2, v4
	v_add_f32_e32 v2, v98, v99
	s_waitcnt vmcnt(12)
	v_mul_f32_e32 v4, v67, v67
	v_mul_f32_e32 v98, v69, v69
	s_waitcnt vmcnt(11)
	v_mul_f32_e32 v99, v63, v63
	s_waitcnt lgkmcnt(0)
	v_mul_f32_e32 v119, v65, v65
	s_waitcnt vmcnt(10)
	v_mul_f32_e32 v120, v59, v59
	v_mul_f32_e32 v121, v61, v61
	v_fmac_f32_e32 v4, v66, v66
	v_fmac_f32_e32 v98, v68, v68
	v_fmac_f32_e32 v99, v62, v62
	v_fmac_f32_e32 v119, v64, v64
	s_waitcnt vmcnt(9)
	v_mul_f32_e32 v122, v55, v55
	v_mul_f32_e32 v123, v57, v57
	v_fmac_f32_e32 v120, v58, v58
	v_fmac_f32_e32 v121, v60, v60
	v_add_f32_e32 v4, v4, v98
	v_add_f32_e32 v98, v99, v119
	v_fmac_f32_e32 v122, v54, v54
	v_fmac_f32_e32 v123, v56, v56
	v_add_f32_e32 v99, v120, v121
	v_add_f32_e32 v4, v4, v98
	v_add_f32_e32 v119, v122, v123
	v_add_f32_e32 v4, v4, v99
	v_add_f32_e32 v4, v4, v119
	ds_bpermute_b32 v99, v111, v4
	v_mul_f32_e32 v5, v7, v7
	v_fmac_f32_e32 v5, v6, v6
	v_cvt_pk_bf16_f32 v66, v66, v67
	v_cvt_pk_bf16_f32 v67, v68, v69
	s_waitcnt lgkmcnt(0)
	v_add_f32_e32 v4, v4, v99
	ds_bpermute_b32 v99, v112, v4
	s_waitcnt lgkmcnt(0)
	v_add_f32_e32 v4, v4, v99
	ds_bpermute_b32 v99, v113, v4
	s_waitcnt lgkmcnt(0)
	v_add_f32_e32 v4, v4, v99
	ds_bpermute_b32 v99, v114, v4
	s_waitcnt lgkmcnt(0)
	v_add_f32_e32 v4, v4, v99
	ds_bpermute_b32 v99, v115, v4
	s_waitcnt vmcnt(8)
	v_mul_f32_e32 v124, v51, v51
	v_mul_f32_e32 v125, v53, v53
	s_waitcnt vmcnt(7)
	v_mul_f32_e32 v126, v47, v47
	v_mul_f32_e32 v127, v49, v49
	v_fmac_f32_e32 v124, v50, v50
	v_fmac_f32_e32 v125, v52, v52
	v_fmac_f32_e32 v126, v46, v46
	v_fmac_f32_e32 v127, v48, v48
	s_waitcnt vmcnt(4)
	v_mul_f32_e32 v120, v35, v35
	v_mul_f32_e32 v121, v37, v37
	s_waitcnt vmcnt(3)
	v_mul_f32_e32 v122, v31, v31
	v_mul_f32_e32 v123, v33, v33
	s_waitcnt vmcnt(2)
	v_mul_f32_e32 v132, v27, v27
	v_mul_f32_e32 v133, v29, v29
	v_add_f32_e32 v98, v124, v125
	v_add_f32_e32 v119, v126, v127
	v_fmac_f32_e32 v120, v34, v34
	v_fmac_f32_e32 v121, v36, v36
	v_fmac_f32_e32 v122, v30, v30
	v_fmac_f32_e32 v123, v32, v32
	v_fmac_f32_e32 v132, v26, v26
	v_fmac_f32_e32 v133, v28, v28
	v_add_f32_e32 v98, v98, v119
	v_add_f32_e32 v119, v120, v121
	v_add_f32_e32 v120, v122, v123
	v_add_f32_e32 v121, v132, v133
	v_add_f32_e32 v119, v119, v120
	v_add_f32_e32 v119, v119, v121
	v_add_f32_e32 v119, v119, v2
	s_waitcnt lgkmcnt(0)
	v_add_f32_e32 v2, v4, v99
	v_mul_f32_e32 v99, v9, v9
	v_fmac_f32_e32 v99, v8, v8
	v_add_f32_e32 v5, v5, v99
	v_add_f32_e32 v5, v118, v5
	s_waitcnt vmcnt(1)
	v_mul_f32_e32 v99, v19, v19
	v_mul_f32_e32 v118, v21, v21
	v_fmac_f32_e32 v99, v18, v18
	v_fmac_f32_e32 v118, v20, v20
	v_mul_f32_e32 v128, v43, v43
	v_mul_f32_e32 v129, v45, v45
	v_add_f32_e32 v99, v99, v118
	v_mul_f32_e32 v130, v39, v39
	v_mul_f32_e32 v131, v41, v41
	v_fmac_f32_e32 v128, v42, v42
	v_fmac_f32_e32 v129, v44, v44
	v_add_f32_e32 v5, v5, v99
	s_waitcnt vmcnt(0)
	v_mul_f32_e32 v99, v15, v15
	v_mul_f32_e32 v118, v17, v17
	v_fmac_f32_e32 v130, v38, v38
	v_fmac_f32_e32 v131, v40, v40
	v_add_f32_e32 v124, v128, v129
	v_fmac_f32_e32 v99, v14, v14
	v_fmac_f32_e32 v118, v16, v16
	v_add_f32_e32 v125, v130, v131
	v_add_f32_e32 v98, v98, v124
	v_add_f32_e32 v99, v99, v118
	v_add_f32_e32 v98, v98, v125
	v_add_f32_e32 v5, v5, v99
	ds_bpermute_b32 v120, v111, v98
	ds_bpermute_b32 v121, v111, v119
	ds_bpermute_b32 v99, v111, v5
	ds_bpermute_b32 v4, v116, v2
	s_waitcnt lgkmcnt(3)
	v_add_f32_e32 v98, v98, v120
	s_waitcnt lgkmcnt(2)
	v_add_f32_e32 v119, v119, v121
	s_waitcnt lgkmcnt(1)
	v_add_f32_e32 v5, v5, v99
	ds_bpermute_b32 v118, v112, v98
	ds_bpermute_b32 v120, v112, v119
	ds_bpermute_b32 v99, v112, v5
	s_waitcnt lgkmcnt(2)
	v_add_f32_e32 v98, v98, v118
	s_waitcnt lgkmcnt(1)
	v_add_f32_e32 v119, v119, v120
	s_waitcnt lgkmcnt(0)
	v_add_f32_e32 v5, v5, v99
	ds_bpermute_b32 v118, v113, v98
	ds_bpermute_b32 v120, v113, v119
	ds_bpermute_b32 v99, v113, v5
	s_waitcnt lgkmcnt(2)
	v_add_f32_e32 v98, v98, v118
	s_waitcnt lgkmcnt(1)
	v_add_f32_e32 v119, v119, v120
	s_waitcnt lgkmcnt(0)
	v_add_f32_e32 v5, v5, v99
	ds_bpermute_b32 v118, v114, v98
	ds_bpermute_b32 v120, v114, v119
	ds_bpermute_b32 v99, v114, v5
	s_waitcnt lgkmcnt(2)
	v_add_f32_e32 v98, v98, v118
	s_waitcnt lgkmcnt(1)
	v_add_f32_e32 v119, v119, v120
	s_waitcnt lgkmcnt(0)
	v_add_f32_e32 v5, v5, v99
	ds_bpermute_b32 v118, v115, v98
	ds_bpermute_b32 v120, v115, v119
	ds_bpermute_b32 v99, v115, v5
	s_waitcnt lgkmcnt(2)
	v_add_f32_e32 v122, v98, v118
	s_waitcnt lgkmcnt(1)
	v_add_f32_e32 v120, v119, v120
	s_waitcnt lgkmcnt(0)
	v_add_f32_e32 v118, v5, v99
	ds_bpermute_b32 v123, v116, v122
	ds_bpermute_b32 v121, v116, v120
	ds_bpermute_b32 v119, v116, v118
	v_lshl_add_u64 v[98:99], s[46:47], 0, v[94:95]
	v_add_co_u32_e32 v68, vcc, s3, v98
	s_nop 1
	v_addc_co_u32_e32 v69, vcc, 0, v99, vcc
	global_store_dwordx2 v[68:69], v[66:67], off
	v_cvt_pk_bf16_f32 v62, v62, v63
	v_cvt_pk_bf16_f32 v63, v64, v65
	global_store_dwordx2 v[68:69], v[62:63], off offset:512
	v_cvt_pk_bf16_f32 v58, v58, v59
	v_cvt_pk_bf16_f32 v59, v60, v61
	global_store_dwordx2 v[68:69], v[58:59], off offset:1024
	v_cvt_pk_bf16_f32 v54, v54, v55
	v_cvt_pk_bf16_f32 v55, v56, v57
	global_store_dwordx2 v[68:69], v[54:55], off offset:1536
	v_lshl_add_u64 v[54:55], s[46:47], 0, v[96:97]
	s_and_saveexec_b64 s[30:31], s[8:9]
	s_cbranch_execz .LBB0_47
	v_add_co_u32_e32 v56, vcc, 0x100000, v54
	v_add_f32_e32 v2, v2, v4
	s_nop 0
	v_addc_co_u32_e32 v57, vcc, 0, v55, vcc
	v_mov_b32_e32 v4, v3
	v_mov_b32_e32 v5, v3
	global_store_dwordx4 v[56:57], v[2:5], off

.LBB0_1260:
	v_add_co_u32_e32 v24, vcc, s9, v18
	v_lshl_add_u64 v[30:31], s[2:3], 0, v[22:23]
	s_nop 0
	v_addc_co_u32_e32 v25, vcc, -1, v19, vcc
	v_add_co_u32_e32 v26, vcc, s10, v18
	v_lshl_add_u64 v[28:29], s[2:3], 0, v[20:21]
	s_nop 0
	v_addc_co_u32_e32 v27, vcc, -1, v19, vcc
	v_add_co_u32_e32 v32, vcc, s11, v18
	v_lshl_add_u64 v[78:79], v[28:29], 0, s[6:7]
	s_nop 0
	v_addc_co_u32_e32 v33, vcc, -1, v19, vcc
	v_add_co_u32_e32 v74, vcc, 0x6000000, v30
	v_add_co_u32_e64 v58, s[0:1], s8, v30
	s_nop 0
	v_addc_co_u32_e32 v75, vcc, 0, v31, vcc
	v_add_co_u32_e32 v80, vcc, 0x100000, v28
	v_addc_co_u32_e64 v59, s[0:1], 0, v31, s[0:1]
	global_load_dwordx4 v[34:37], v[78:79], off offset:16
	global_load_dwordx4 v[38:41], v[78:79], off offset:32
	global_load_dwordx4 v[42:45], v[58:59], off
	global_load_dwordx4 v[46:49], v[58:59], off offset:1024
	global_load_dwordx4 v[50:53], v[58:59], off offset:2048
	global_load_dwordx4 v[54:57], v[58:59], off offset:3072
	v_addc_co_u32_e32 v81, vcc, 0, v29, vcc
	global_load_dwordx4 v[58:61], v[74:75], off
	global_load_dwordx4 v[62:65], v[74:75], off offset:1024
	global_load_dwordx4 v[66:69], v[74:75], off offset:2048
	global_load_dwordx4 v[70:73], v[74:75], off offset:3072
	global_load_dwordx4 v[28:31], v[80:81], off
	s_nop 0
	global_load_dwordx4 v[74:77], v[78:79], off offset:48
	v_add_u32_e32 v16, s34, v16
	v_cmp_lt_i32_e64 s[0:1], s12, v16
	v_lshl_add_u64 v[20:21], v[20:21], 0, s[36:37]
	v_lshl_add_u64 v[22:23], v[22:23], 0, s[38:39]
	s_or_b64 s[4:5], s[0:1], s[4:5]
	s_waitcnt vmcnt(11)
	v_mov_b32_e32 v78, v35
	v_mov_b32_e32 v79, v36
	v_mov_b32_e32 v35, v37
	s_waitcnt vmcnt(10)
	v_mov_b32_e32 v36, v39
	v_mov_b32_e32 v37, v40
	v_mov_b32_e32 v39, v41
	s_waitcnt vmcnt(7)
	v_lshlrev_b32_e32 v90, 16, v52
	v_and_b32_e32 v91, 0xffff0000, v52
	v_lshlrev_b32_e32 v92, 16, v53
	v_and_b32_e32 v93, 0xffff0000, v53
	s_waitcnt vmcnt(6)
	v_lshlrev_b32_e32 v94, 16, v54
	v_and_b32_e32 v95, 0xffff0000, v54
	v_lshlrev_b32_e32 v96, 16, v55
	v_and_b32_e32 v97, 0xffff0000, v55
	v_pk_add_f32 v[34:35], v[78:79], v[34:35]
	v_pk_add_f32 v[36:37], v[36:37], v[38:39]
	s_waitcnt vmcnt(3)
	v_lshlrev_b32_e32 v52, 16, v68
	v_and_b32_e32 v53, 0xffff0000, v68
	v_lshlrev_b32_e32 v54, 16, v69
	v_and_b32_e32 v55, 0xffff0000, v69
	s_waitcnt vmcnt(1)
	v_mov_b32_e32 v68, v29
	v_mov_b32_e32 v69, v30
	v_mov_b32_e32 v29, v31
	v_add_f32_e32 v34, v34, v35
	v_add_f32_e32 v35, v36, v37
	s_waitcnt vmcnt(0)
	v_mov_b32_e32 v30, v75
	v_mov_b32_e32 v31, v76
	v_mov_b32_e32 v75, v77
	v_pk_add_f32 v[28:29], v[68:69], v[28:29]
	v_fmamk_f32 v34, v34, 0x3a800000, v17
	v_fmamk_f32 v35, v35, 0x3a800000, v17
	v_pk_add_f32 v[30:31], v[30:31], v[74:75]
	v_add_f32_e32 v29, v28, v29
	v_rsq_f32_e32 v28, v34
	v_rsq_f32_e32 v34, v35
	v_add_f32_e32 v30, v30, v31
	v_fmamk_f32 v29, v29, 0x3a800000, v17
	v_fmamk_f32 v30, v30, 0x3a800000, v17
	v_rsq_f32_e32 v68, v29
	v_lshlrev_b32_e32 v98, 16, v56
	v_and_b32_e32 v99, 0xffff0000, v56
	v_lshlrev_b32_e32 v100, 16, v57
	v_and_b32_e32 v101, 0xffff0000, v57
	v_lshlrev_b32_e32 v56, 16, v70
	v_and_b32_e32 v57, 0xffff0000, v70
	v_rsq_f32_e32 v70, v30
	v_lshlrev_b32_e32 v40, 16, v42
	v_and_b32_e32 v41, 0xffff0000, v42
	v_lshlrev_b32_e32 v42, 16, v43
	v_and_b32_e32 v43, 0xffff0000, v43
	v_lshlrev_b32_e32 v80, 16, v44
	v_and_b32_e32 v81, 0xffff0000, v44
	v_lshlrev_b32_e32 v44, 16, v45
	v_and_b32_e32 v45, 0xffff0000, v45
	v_lshlrev_b32_e32 v82, 16, v46
	v_and_b32_e32 v83, 0xffff0000, v46
	v_lshlrev_b32_e32 v46, 16, v47
	v_and_b32_e32 v47, 0xffff0000, v47
	v_lshlrev_b32_e32 v84, 16, v48
	v_and_b32_e32 v85, 0xffff0000, v48
	v_lshlrev_b32_e32 v86, 16, v50
	v_and_b32_e32 v87, 0xffff0000, v50
	v_lshlrev_b32_e32 v88, 16, v51
	v_and_b32_e32 v89, 0xffff0000, v51
	v_lshlrev_b32_e32 v78, 16, v58
	v_and_b32_e32 v79, 0xffff0000, v58
	v_lshlrev_b32_e32 v102, 16, v59
	v_and_b32_e32 v103, 0xffff0000, v59
	v_lshlrev_b32_e32 v104, 16, v60
	v_and_b32_e32 v105, 0xffff0000, v60
	v_lshlrev_b32_e32 v106, 16, v61
	v_and_b32_e32 v107, 0xffff0000, v61
	v_lshlrev_b32_e32 v38, 16, v66
	v_and_b32_e32 v39, 0xffff0000, v66
	v_lshlrev_b32_e32 v50, 16, v67
	v_and_b32_e32 v51, 0xffff0000, v67
	v_lshlrev_b32_e32 v58, 16, v71
	v_and_b32_e32 v59, 0xffff0000, v71
	v_lshlrev_b32_e32 v60, 16, v72
	v_and_b32_e32 v61, 0xffff0000, v72
	v_lshlrev_b32_e32 v66, 16, v73
	v_and_b32_e32 v67, 0xffff0000, v73
	v_lshlrev_b32_e32 v48, 16, v49
	v_and_b32_e32 v49, 0xffff0000, v49
	v_pk_mul_f32 v[36:37], v[28:29], v[38:39] op_sel_hi:[0,1]
	v_pk_mul_f32 v[30:31], v[28:29], v[50:51] op_sel_hi:[0,1]
	v_pk_mul_f32 v[38:39], v[28:29], v[52:53] op_sel_hi:[0,1]
	v_pk_mul_f32 v[50:51], v[28:29], v[54:55] op_sel_hi:[0,1]
	v_pk_mul_f32 v[52:53], v[28:29], v[56:57] op_sel_hi:[0,1]
	v_pk_mul_f32 v[54:55], v[28:29], v[58:59] op_sel_hi:[0,1]
	v_pk_mul_f32 v[56:57], v[28:29], v[60:61] op_sel_hi:[0,1]
	v_pk_mul_f32 v[58:59], v[28:29], v[66:67] op_sel_hi:[0,1]
	v_pk_mul_f32 v[60:61], v[34:35], v[40:41] op_sel_hi:[0,1]
	v_pk_mul_f32 v[66:67], v[34:35], v[42:43] op_sel_hi:[0,1]
	v_pk_mul_f32 v[72:73], v[34:35], v[80:81] op_sel_hi:[0,1]
	v_pk_mul_f32 v[74:75], v[34:35], v[44:45] op_sel_hi:[0,1]
	v_pk_mul_f32 v[76:77], v[34:35], v[82:83] op_sel_hi:[0,1]
	v_pk_mul_f32 v[80:81], v[34:35], v[46:47] op_sel_hi:[0,1]
	v_pk_mul_f32 v[82:83], v[34:35], v[84:85] op_sel_hi:[0,1]
	v_lshlrev_b32_e32 v108, 16, v62
	v_and_b32_e32 v109, 0xffff0000, v62
	v_lshlrev_b32_e32 v62, 16, v63
	v_and_b32_e32 v63, 0xffff0000, v63
	v_lshlrev_b32_e32 v110, 16, v64
	v_and_b32_e32 v111, 0xffff0000, v64
	v_lshlrev_b32_e32 v64, 16, v65
	v_and_b32_e32 v65, 0xffff0000, v65
	v_pk_mul_f32 v[84:85], v[34:35], v[48:49] op_sel_hi:[0,1]
	v_pk_mul_f32 v[30:31], v[6:7], v[30:31]
	v_pk_mul_f32 v[28:29], v[4:5], v[36:37]
	v_pk_mul_f32 v[36:37], v[2:3], v[50:51]
	v_pk_mul_f32 v[34:35], v[0:1], v[38:39]
	v_pk_mul_f32 v[40:41], v[14:15], v[54:55]
	v_pk_mul_f32 v[38:39], v[12:13], v[52:53]
	v_pk_mul_f32 v[44:45], v[10:11], v[58:59]
	v_pk_mul_f32 v[42:43], v[8:9], v[56:57]
	v_pk_mul_f32 v[48:49], v[6:7], v[66:67]
	v_pk_mul_f32 v[46:47], v[4:5], v[60:61]
	v_pk_mul_f32 v[52:53], v[2:3], v[74:75]
	v_pk_mul_f32 v[50:51], v[0:1], v[72:73]
	v_pk_mul_f32 v[56:57], v[14:15], v[80:81]
	v_pk_mul_f32 v[54:55], v[12:13], v[76:77]
	v_pk_mul_f32 v[58:59], v[8:9], v[82:83]
	v_pk_mul_f32 v[66:67], v[68:69], v[78:79] op_sel_hi:[0,1]
	v_pk_mul_f32 v[72:73], v[68:69], v[102:103] op_sel_hi:[0,1]
	v_pk_mul_f32 v[60:61], v[10:11], v[84:85]
	v_pk_mul_f32 v[74:75], v[68:69], v[104:105] op_sel_hi:[0,1]
	v_pk_mul_f32 v[76:77], v[68:69], v[106:107] op_sel_hi:[0,1]
	v_pk_mul_f32 v[78:79], v[68:69], v[108:109] op_sel_hi:[0,1]
	v_pk_mul_f32 v[62:63], v[68:69], v[62:63] op_sel_hi:[0,1]
	v_pk_mul_f32 v[80:81], v[68:69], v[110:111] op_sel_hi:[0,1]
	v_pk_mul_f32 v[64:65], v[68:69], v[64:65] op_sel_hi:[0,1]
	global_store_dwordx4 v[26:27], v[28:31], off offset:-2064 nt
	global_store_dwordx4 v[26:27], v[34:37], off offset:-2048 nt
	global_store_dwordx4 v[26:27], v[38:41], off offset:-16 nt
	global_store_dwordx4 v[26:27], v[42:45], off nt
	global_store_dwordx4 v[32:33], v[46:49], off offset:-2064 nt
	global_store_dwordx4 v[32:33], v[50:53], off offset:-2048 nt
	global_store_dwordx4 v[32:33], v[54:57], off offset:-16 nt
	global_store_dwordx4 v[18:19], v[58:61], off offset:-4096 nt
	v_pk_mul_f32 v[44:45], v[70:71], v[86:87] op_sel_hi:[0,1]
	v_pk_mul_f32 v[46:47], v[70:71], v[88:89] op_sel_hi:[0,1]
	v_pk_mul_f32 v[48:49], v[70:71], v[90:91] op_sel_hi:[0,1]
	v_pk_mul_f32 v[50:51], v[70:71], v[92:93] op_sel_hi:[0,1]
	v_pk_mul_f32 v[52:53], v[70:71], v[94:95] op_sel_hi:[0,1]
	v_pk_mul_f32 v[54:55], v[70:71], v[96:97] op_sel_hi:[0,1]
	v_pk_mul_f32 v[56:57], v[70:71], v[98:99] op_sel_hi:[0,1]
	v_pk_mul_f32 v[58:59], v[70:71], v[100:101] op_sel_hi:[0,1]
	v_pk_mul_f32 v[30:31], v[6:7], v[72:73]
	v_pk_mul_f32 v[28:29], v[4:5], v[66:67]
	v_pk_mul_f32 v[34:35], v[2:3], v[76:77]
	v_pk_mul_f32 v[32:33], v[0:1], v[74:75]
	v_pk_mul_f32 v[38:39], v[14:15], v[62:63]
	v_pk_mul_f32 v[36:37], v[12:13], v[78:79]
	v_pk_mul_f32 v[42:43], v[10:11], v[64:65]
	v_pk_mul_f32 v[40:41], v[8:9], v[80:81]
	v_pk_mul_f32 v[46:47], v[6:7], v[46:47]
	v_pk_mul_f32 v[44:45], v[4:5], v[44:45]
	v_pk_mul_f32 v[50:51], v[2:3], v[50:51]
	v_pk_mul_f32 v[48:49], v[0:1], v[48:49]
	v_pk_mul_f32 v[54:55], v[14:15], v[54:55]
	v_pk_mul_f32 v[52:53], v[12:13], v[52:53]
	v_pk_mul_f32 v[58:59], v[10:11], v[58:59]
	v_pk_mul_f32 v[56:57], v[8:9], v[56:57]
	global_store_dwordx4 v[24:25], v[28:31], off offset:-2064 nt
	global_store_dwordx4 v[24:25], v[32:35], off offset:-2048 nt
	global_store_dwordx4 v[24:25], v[36:39], off offset:-16 nt
	global_store_dwordx4 v[26:27], v[40:43], off offset:-4096 nt
	global_store_dwordx4 v[18:19], v[44:47], off offset:-2064 nt
	global_store_dwordx4 v[18:19], v[48:51], off offset:-2048 nt
	global_store_dwordx4 v[18:19], v[52:55], off offset:-16 nt
	global_store_dwordx4 v[18:19], v[56:59], off nt
	v_lshl_add_u64 v[18:19], v[18:19], 0, s[40:41]
	s_andn2_b64 exec, exec, s[4:5]
	s_cbranch_execnz .LBB0_1260
